# P10 attention output stores widened (permlane16_swap) + P4 mem rms gamma loads hoisted out of the load-wait-store chain
# baseline (speedup 1.0000x reference)
; __device__ __forceinline__ void rms_row2048(const float* xrow, const float* g, bf16_t* orow, int lane) {
;     const f32x4* xr = (const f32x4*)xrow + lane; const f32x4* gr = (const f32x4*)g + lane;
;     f32x4 v[8]; float s = 0.f;
; #pragma unroll
;     for (int j = 0; j < 8; ++j) { v[j] = xr[64 * j]; s += (v[j].x * v[j].x + v[j].y * v[j].y) + (v[j].z * v[j].z + v[j].w * v[j].w); }
.LBB0_605:
	v_add_co_u32_e32 v36, vcc, 0xfffff000, v12
	global_load_dwordx4 v[16:19], v[12:13], off offset:-3072
	global_load_dwordx4 v[20:23], v[12:13], off offset:-2048
	global_load_dwordx4 v[24:27], v[12:13], off offset:-1024
	v_addc_co_u32_e32 v37, vcc, -1, v13, vcc
	global_load_dwordx4 v[28:31], v[36:37], off offset:-3072
	global_load_dwordx4 v[32:35], v[36:37], off offset:-2048
	s_nop 0
	global_load_dwordx4 v[36:39], v[36:37], off offset:-1024
	s_nop 0
	global_load_dwordx4 v[40:43], v[12:13], off offset:-4096
	global_load_dwordx4 v[44:47], v[12:13], off
	global_load_dwordx4 v[48:51], v[0:1], off
	global_load_dwordx4 v[206:209], v[0:1], off offset:1024
	global_load_dwordx4 v[210:213], v[0:1], off offset:2048
	global_load_dwordx4 v[214:217], v[0:1], off offset:3072
	global_load_dwordx4 v[218:221], v[2:3], off
	global_load_dwordx4 v[222:225], v[4:5], off
	global_load_dwordx4 v[226:229], v[6:7], off
	global_load_dwordx4 v[230:233], v[8:9], off
	s_add_i32 s7, s7, s96
	s_cmpk_gt_i32 s7, 0x7ff
	v_lshl_add_u64 v[12:13], v[12:13], 0, s[2:3]
	s_waitcnt vmcnt(0)
; __device__ __forceinline__ unsigned pk2(float lo, float hi) { f32x2_t v = {lo, hi}; bf16x2_t b = __builtin_convertvector(v, bf16x2_t); return __builtin_bit_cast(unsigned, b); }
; __device__ __forceinline__ void rms_row2048(const float* xrow, const float* g, bf16_t* orow, int lane) {
;     ...
;     for (int j = 0; j < 8; ++j) { v[j] = xr[64 * j]; s += (v[j].x * v[j].x + v[j].y * v[j].y) + (v[j].z * v[j].z + v[j].w * v[j].w); }
;     const float r = rsqrtf(wave_sum(s) * (1.f / 2048.f) + EPS);
;     u32x2* o8 = (u32x2*)orow + lane;
; #pragma unroll
;     for (int j = 0; j < 8; ++j) { const f32x4 gg = gr[64 * j]; u32x2 w; w.x = pk2(v[j].x * r * gg.x, v[j].y * r * gg.y); w.y = pk2(v[j].z * r * gg.z, v[j].w * r * gg.w); o8[64 * j] = w; }
	v_mov_b32_e32 v62, v29
	v_pk_mul_f32 v[52:53], v[22:23], v[22:23]
	v_pk_mul_f32 v[54:55], v[20:21], v[20:21]
	v_mul_f32_e32 v56, v25, v25
	v_mul_f32_e32 v58, v27, v27
	v_mul_f32_e32 v73, v46, v46
	v_mul_f32_e32 v80, v47, v47
	v_pk_mov_b32 v[60:61], v[54:55], v[52:53] op_sel:[1,0]
	v_mov_b32_e32 v55, v53
	v_pk_fma_f32 v[52:53], v[24:25], v[24:25], v[56:57] op_sel_hi:[1,1,0]
	v_pk_fma_f32 v[56:57], v[26:27], v[26:27], v[58:59] op_sel_hi:[1,1,0]
	v_mov_b32_e32 v63, v33
	v_mov_b32_e32 v66, v31
	v_mov_b32_e32 v67, v35
	v_mov_b32_e32 v58, v28
	v_mov_b32_e32 v59, v32
	v_mov_b32_e32 v64, v30
	v_mov_b32_e32 v65, v34
	v_pk_mul_f32 v[68:69], v[38:39], v[38:39]
	v_pk_mul_f32 v[70:71], v[36:37], v[36:37]
	v_pk_add_f32 v[54:55], v[60:61], v[54:55]
	v_mov_b32_e32 v53, v73
	v_mov_b32_e32 v57, v80
	v_pk_mul_f32 v[60:61], v[62:63], v[62:63]
	v_pk_mul_f32 v[62:63], v[66:67], v[66:67]
	v_pk_mov_b32 v[66:67], v[70:71], v[68:69] op_sel:[1,0]
	v_mov_b32_e32 v71, v69
	v_pk_add_f32 v[52:53], v[52:53], v[56:57]
	v_pk_fma_f32 v[56:57], v[58:59], v[58:59], v[60:61]
	v_pk_fma_f32 v[58:59], v[64:65], v[64:65], v[62:63]
	v_mul_f32_e32 v75, v17, v17
	v_mul_f32_e32 v72, v41, v41
	v_mul_f32_e32 v74, v43, v43
	v_pk_add_f32 v[60:61], v[66:67], v[70:71]
	v_pk_add_f32 v[56:57], v[56:57], v[58:59]
	v_mul_f32_e32 v15, v16, v16
	v_mul_f32_e32 v76, v18, v18
	v_mul_f32_e32 v77, v19, v19
	v_pk_fma_f32 v[68:69], v[40:41], v[40:41], v[72:73] op_sel_hi:[1,1,0]
	v_pk_fma_f32 v[72:73], v[42:43], v[42:43], v[74:75] op_sel_hi:[1,1,0]
	v_pk_add_f32 v[58:59], v[60:61], v[60:61] op_sel:[0,1] op_sel_hi:[1,0]
	v_pk_add_f32 v[56:57], v[56:57], v[56:57] op_sel:[0,1] op_sel_hi:[1,0]
	v_mov_b32_e32 v69, v76
	v_mov_b32_e32 v73, v77
	v_mov_b32_e32 v59, v75
	v_mov_b32_e32 v57, v15
	v_pk_add_f32 v[60:61], v[68:69], v[72:73]
	v_pk_add_f32 v[56:57], v[56:57], v[58:59]
	v_mul_f32_e32 v78, v44, v44
	v_pk_add_f32 v[56:57], v[56:57], v[60:61]
	v_mul_f32_e32 v79, v45, v45
	v_pk_add_f32 v[54:55], v[54:55], v[54:55] op_sel:[0,1] op_sel_hi:[1,0]
	v_pk_add_f32 v[56:57], v[56:57], v[56:57] op_sel:[0,1] op_sel_hi:[1,0]
	v_mov_b32_e32 v55, v79
	v_mov_b32_e32 v57, v78
	v_pk_add_f32 v[54:55], v[56:57], v[54:55]
	s_nop 0
	v_pk_add_f32 v[52:53], v[54:55], v[52:53]
	s_nop 0
	v_add_f32_e32 v15, v52, v53
	s_nop 1
	v_add_f32_dpp v15, v15, v15 quad_perm:[1,0,3,2] row_mask:0xf bank_mask:0xf bound_ctrl:1
	s_nop 1
	v_add_f32_dpp v15, v15, v15 quad_perm:[2,3,0,1] row_mask:0xf bank_mask:0xf bound_ctrl:1
	s_nop 1
	v_add_f32_dpp v15, v15, v15 row_half_mirror row_mask:0xf bank_mask:0xf bound_ctrl:1
	s_nop 1
	v_add_f32_dpp v15, v15, v15 row_mirror row_mask:0xf bank_mask:0xf bound_ctrl:1
	s_nop 0
	v_readlane_b32 s10, v15, 16
	v_readlane_b32 s11, v15, 48
	v_readlane_b32 s8, v15, 0
	v_readlane_b32 s9, v15, 32
	v_mov_b32_e32 v52, s10
	v_mov_b32_e32 v53, s11
	v_pk_add_f32 v[52:53], s[8:9], v[52:53]
	s_nop 0
	v_add_f32_e32 v15, v52, v53
	v_fmamk_f32 v15, v15, 0x3a000000, v14
	v_mul_f32_e32 v52, 0x4b800000, v15
	v_cmp_gt_f32_e32 vcc, s6, v15
	s_nop 1
	v_cndmask_b32_e32 v15, v15, v52, vcc
	v_rsq_f32_e32 v15, v15
	s_nop 0
	v_mul_f32_e32 v52, 0x45800000, v15
	v_cndmask_b32_e32 v52, v15, v52, vcc
	v_pk_mul_f32 v[28:29], v[28:29], v[52:53] op_sel_hi:[1,0]
	v_pk_mul_f32 v[30:31], v[30:31], v[52:53] op_sel_hi:[1,0]
	v_pk_mul_f32 v[28:29], v[48:49], v[28:29]
	v_pk_mul_f32 v[30:31], v[50:51], v[30:31]
	v_cvt_pk_bf16_f32 v28, v28, v29
	v_cvt_pk_bf16_f32 v29, v30, v31
	global_store_dwordx2 v[10:11], v[28:29], off offset:-3584
	v_mov_b64_e32 v[28:29], v[206:207]
	v_mov_b64_e32 v[30:31], v[208:209]
	v_pk_mul_f32 v[32:33], v[32:33], v[52:53] op_sel_hi:[1,0]
	v_pk_mul_f32 v[34:35], v[34:35], v[52:53] op_sel_hi:[1,0]
	v_pk_mul_f32 v[16:17], v[16:17], v[52:53] op_sel_hi:[1,0]
	v_pk_mul_f32 v[18:19], v[18:19], v[52:53] op_sel_hi:[1,0]
	v_pk_mul_f32 v[20:21], v[20:21], v[52:53] op_sel_hi:[1,0]
	v_pk_mul_f32 v[22:23], v[22:23], v[52:53] op_sel_hi:[1,0]
	s_nop 0
	v_pk_mul_f32 v[28:29], v[28:29], v[32:33]
	v_pk_mul_f32 v[30:31], v[30:31], v[34:35]
	v_cvt_pk_bf16_f32 v28, v28, v29
	v_cvt_pk_bf16_f32 v29, v30, v31
	global_store_dwordx2 v[10:11], v[28:29], off offset:-3072
	v_mov_b64_e32 v[28:29], v[210:211]
	v_mov_b64_e32 v[30:31], v[212:213]
	v_pk_mul_f32 v[32:33], v[36:37], v[52:53] op_sel_hi:[1,0]
	v_pk_mul_f32 v[34:35], v[38:39], v[52:53] op_sel_hi:[1,0]
	s_nop 0
	v_pk_mul_f32 v[28:29], v[28:29], v[32:33]
	v_pk_mul_f32 v[30:31], v[30:31], v[34:35]
	v_cvt_pk_bf16_f32 v28, v28, v29
	v_cvt_pk_bf16_f32 v29, v30, v31
	global_store_dwordx2 v[10:11], v[28:29], off offset:-2560
	v_mov_b64_e32 v[28:29], v[214:215]
	v_mov_b64_e32 v[30:31], v[216:217]
	v_pk_mul_f32 v[32:33], v[40:41], v[52:53] op_sel_hi:[1,0]
	v_pk_mul_f32 v[34:35], v[42:43], v[52:53] op_sel_hi:[1,0]
	s_nop 0
	v_pk_mul_f32 v[28:29], v[28:29], v[32:33]
	v_pk_mul_f32 v[30:31], v[30:31], v[34:35]
	v_cvt_pk_bf16_f32 v28, v28, v29
	v_cvt_pk_bf16_f32 v29, v30, v31
	global_store_dwordx2 v[10:11], v[28:29], off offset:-2048
	v_mov_b64_e32 v[28:29], v[218:219]
	v_mov_b64_e32 v[30:31], v[220:221]
	s_nop 0
	v_pk_mul_f32 v[16:17], v[28:29], v[16:17]
	v_pk_mul_f32 v[18:19], v[30:31], v[18:19]
	v_cvt_pk_bf16_f32 v16, v16, v17
	v_cvt_pk_bf16_f32 v17, v18, v19
	global_store_dwordx2 v[10:11], v[16:17], off offset:-1536
	v_mov_b64_e32 v[16:17], v[222:223]
	v_mov_b64_e32 v[18:19], v[224:225]
	s_nop 0
	v_pk_mul_f32 v[16:17], v[20:21], v[16:17]
	v_pk_mul_f32 v[18:19], v[22:23], v[18:19]
	v_cvt_pk_bf16_f32 v16, v16, v17
	v_cvt_pk_bf16_f32 v17, v18, v19
	global_store_dwordx2 v[10:11], v[16:17], off offset:-1024
	v_mov_b64_e32 v[16:17], v[226:227]
	v_mov_b64_e32 v[18:19], v[228:229]
	v_pk_mul_f32 v[20:21], v[24:25], v[52:53] op_sel_hi:[1,0]
	v_pk_mul_f32 v[22:23], v[26:27], v[52:53] op_sel_hi:[1,0]
	s_nop 0
	v_pk_mul_f32 v[16:17], v[20:21], v[16:17]
	v_pk_mul_f32 v[18:19], v[22:23], v[18:19]
	v_cvt_pk_bf16_f32 v16, v16, v17
	v_cvt_pk_bf16_f32 v17, v18, v19
	global_store_dwordx2 v[10:11], v[16:17], off offset:-512
	v_mov_b64_e32 v[16:17], v[230:231]
	v_mov_b64_e32 v[18:19], v[232:233]
	v_pk_mul_f32 v[20:21], v[44:45], v[52:53] op_sel_hi:[1,0]
	v_pk_mul_f32 v[22:23], v[46:47], v[52:53] op_sel_hi:[1,0]
	s_nop 0
	v_pk_mul_f32 v[16:17], v[20:21], v[16:17]
	v_pk_mul_f32 v[18:19], v[22:23], v[18:19]
	v_cvt_pk_bf16_f32 v16, v16, v17
	v_cvt_pk_bf16_f32 v17, v18, v19
	global_store_dwordx2 v[10:11], v[16:17], off
	v_lshl_add_u64 v[10:11], v[10:11], 0, s[0:1]
	s_cbranch_scc0 .LBB0_605

; __device__ __forceinline__ unsigned pk2(float lo, float hi) { f32x2_t v = {lo, hi}; bf16x2_t b = __builtin_convertvector(v, bf16x2_t); return __builtin_bit_cast(unsigned, b); }
; __device__ __forceinline__ float xor16_sum(float v) { float a = v, b = v; swap16(a, b); return a + b; }
; __device__ __forceinline__ float xor32_sum(float v) { float a = v, b = v; swap32(a, b); return a + b; }
; template <int DQK, int QF>
; __device__ __forceinline__ void attn_unit_dma(LAS unsigned char* lds, const bf16_t* Qp, int ldq, const bf16_t* Kp, int ldk, const bf16_t* VTp, int ldvt, bf16_t* Op, int ldo, int nkt, int wave_last, const float* qgam, float qscale) {
;     ...
; #pragma unroll
;     for (int qf = 0; qf < QF; ++qf) {
;         float l = lrun[qf]; l = xor16_sum(l); l = xor32_sum(l);
;         const float inv = 1.f / l;
;         bf16_t* op = Op + (size_t)(16 * QF * wid + 16 * qf + fr) * ldo + 4 * fq;
; #pragma unroll
;         for (int mv = 0; mv < 8; ++mv) { u32x2 w; w.x = pk2(o[qf][mv][0] * inv, o[qf][mv][1] * inv); w.y = pk2(o[qf][mv][2] * inv, o[qf][mv][3] * inv); *(u32x2*)(op + 16 * mv) = w; }
;     }
.LBB0_1469:
	v_mov_b32_e32 v0, v167
	s_nop 1
	v_permlane16_swap_b32 v167, v0
	s_add_u32 s2, s64, s28
	v_add_f32_e32 v0, v167, v0
	v_mov_b32_e32 v1, v0
	s_nop 1
	v_permlane32_swap_b32 v0, v1
	s_addc_u32 s3, s65, s29
	v_add_f32_e32 v2, v0, v1
	v_div_scale_f32 v3, s[4:5], v2, v2, 1.0
	v_rcp_f32_e32 v4, v3
	s_add_u32 s2, s2, s34
	s_addc_u32 s3, s3, 0
	v_mov_b32_e32 v157, v151
	v_fma_f32 v5, -v3, v4, 1.0
	v_fmac_f32_e32 v4, v5, v4
	v_div_scale_f32 v5, vcc, 1.0, v2, 1.0
	v_mul_f32_e32 v6, v5, v4
	v_fma_f32 v7, -v3, v6, v5
	v_fmac_f32_e32 v6, v7, v4
	v_fma_f32 v3, -v3, v6, v5
	v_div_fmas_f32 v3, v3, v4, v6
	v_div_fixup_f32 v2, v3, v2, 1.0
	v_lshl_add_u64 v[0:1], s[2:3], 0, v[156:157]
	v_lshl_add_u64 v[4:5], v[0:1], 0, v[162:163]
	v_bfe_u32 v14, v184, 4, 1
	v_mul_u32_u24_e32 v14, 24, v14
	v_mov_b32_e32 v15, 0
	v_lshl_add_u64 v[14:15], v[4:5], 0, v[14:15]
	v_pk_mul_f32 v[10:11], v[88:89], v[2:3] op_sel_hi:[1,0]
	v_pk_mul_f32 v[12:13], v[90:91], v[2:3] op_sel_hi:[1,0]
	v_pk_mul_f32 v[6:7], v[92:93], v[2:3] op_sel_hi:[1,0]
	v_pk_mul_f32 v[8:9], v[94:95], v[2:3] op_sel_hi:[1,0]
	v_cvt_pk_bf16_f32 v6, v6, v7
	v_cvt_pk_bf16_f32 v7, v8, v9
	v_cvt_pk_bf16_f32 v8, v10, v11
	v_cvt_pk_bf16_f32 v9, v12, v13
	s_nop 1
	v_permlane16_swap_b32 v6, v8
	v_permlane16_swap_b32 v7, v9
	global_store_dwordx4 v[14:15], v[6:9], off
	v_pk_mul_f32 v[10:11], v[80:81], v[2:3] op_sel_hi:[1,0]
	v_pk_mul_f32 v[12:13], v[82:83], v[2:3] op_sel_hi:[1,0]
	v_pk_mul_f32 v[6:7], v[84:85], v[2:3] op_sel_hi:[1,0]
	v_pk_mul_f32 v[8:9], v[86:87], v[2:3] op_sel_hi:[1,0]
	v_cvt_pk_bf16_f32 v6, v6, v7
	v_cvt_pk_bf16_f32 v7, v8, v9
	v_cvt_pk_bf16_f32 v8, v10, v11
	v_cvt_pk_bf16_f32 v9, v12, v13
	s_nop 1
	v_permlane16_swap_b32 v6, v8
	v_permlane16_swap_b32 v7, v9
	global_store_dwordx4 v[14:15], v[6:9], off offset:64
	v_pk_mul_f32 v[10:11], v[72:73], v[2:3] op_sel_hi:[1,0]
	v_pk_mul_f32 v[12:13], v[74:75], v[2:3] op_sel_hi:[1,0]
	v_pk_mul_f32 v[6:7], v[76:77], v[2:3] op_sel_hi:[1,0]
	v_pk_mul_f32 v[8:9], v[78:79], v[2:3] op_sel_hi:[1,0]
	v_cvt_pk_bf16_f32 v6, v6, v7
	v_cvt_pk_bf16_f32 v7, v8, v9
	v_cvt_pk_bf16_f32 v8, v10, v11
	v_cvt_pk_bf16_f32 v9, v12, v13
	s_nop 1
	v_permlane16_swap_b32 v6, v8
	v_permlane16_swap_b32 v7, v9
	global_store_dwordx4 v[14:15], v[6:9], off offset:128
	s_nop 1
	v_pk_mul_f32 v[6:7], v[68:69], v[2:3] op_sel_hi:[1,0]
	v_pk_mul_f32 v[8:9], v[70:71], v[2:3] op_sel_hi:[1,0]
	v_cvt_pk_bf16_f32 v6, v6, v7
	v_cvt_pk_bf16_f32 v7, v8, v9
	global_store_dwordx2 v[4:5], v[6:7], off offset:192
	v_pk_mul_f32 v[6:7], v[64:65], v[2:3] op_sel_hi:[1,0]
	v_mov_b32_e32 v3, v166
	s_nop 1
	v_permlane16_swap_b32 v166, v3
	v_cvt_pk_bf16_f32 v6, v6, v7
	v_add_f32_e32 v3, v166, v3
	v_mov_b32_e32 v7, v3
	s_nop 1
	v_permlane32_swap_b32 v3, v7
	v_lshl_add_u64 v[0:1], v[0:1], 0, v[160:161]
	v_add_f32_e32 v8, v3, v7
	v_div_scale_f32 v9, s[2:3], v8, v8, 1.0
	v_rcp_f32_e32 v10, v9
	v_pk_mul_f32 v[2:3], v[66:67], v[2:3] op_sel_hi:[1,0]
	s_add_i32 s33, s33, s15
	v_cvt_pk_bf16_f32 v7, v2, v3
	v_fma_f32 v2, -v9, v10, 1.0
	v_fmac_f32_e32 v10, v2, v10
	v_div_scale_f32 v2, vcc, 1.0, v8, 1.0
	v_mul_f32_e32 v3, v2, v10
	global_store_dwordx2 v[4:5], v[6:7], off offset:224
	v_fma_f32 v4, -v9, v3, v2
	v_fmac_f32_e32 v3, v4, v10
	v_fma_f32 v2, -v9, v3, v2
	v_div_fmas_f32 v2, v2, v10, v3
	v_div_fixup_f32 v2, v2, v8, 1.0
	v_bfe_u32 v12, v184, 4, 1
	v_mul_u32_u24_e32 v12, 24, v12
	v_mov_b32_e32 v13, 0
	v_lshl_add_u64 v[12:13], v[0:1], 0, v[12:13]
	v_pk_mul_f32 v[8:9], v[56:57], v[2:3] op_sel_hi:[1,0]
	v_pk_mul_f32 v[10:11], v[58:59], v[2:3] op_sel_hi:[1,0]
	v_pk_mul_f32 v[4:5], v[60:61], v[2:3] op_sel_hi:[1,0]
	v_pk_mul_f32 v[6:7], v[62:63], v[2:3] op_sel_hi:[1,0]
	v_cvt_pk_bf16_f32 v4, v4, v5
	v_cvt_pk_bf16_f32 v5, v6, v7
	v_cvt_pk_bf16_f32 v6, v8, v9
	v_cvt_pk_bf16_f32 v7, v10, v11
	s_nop 1
	v_permlane16_swap_b32 v4, v6
	v_permlane16_swap_b32 v5, v7
	global_store_dwordx4 v[12:13], v[4:7], off
	v_pk_mul_f32 v[8:9], v[48:49], v[2:3] op_sel_hi:[1,0]
	v_pk_mul_f32 v[10:11], v[50:51], v[2:3] op_sel_hi:[1,0]
	v_pk_mul_f32 v[4:5], v[52:53], v[2:3] op_sel_hi:[1,0]
	v_pk_mul_f32 v[6:7], v[54:55], v[2:3] op_sel_hi:[1,0]
	v_cvt_pk_bf16_f32 v4, v4, v5
	v_cvt_pk_bf16_f32 v5, v6, v7
	v_cvt_pk_bf16_f32 v6, v8, v9
	v_cvt_pk_bf16_f32 v7, v10, v11
	s_nop 1
	v_permlane16_swap_b32 v4, v6
	v_permlane16_swap_b32 v5, v7
	global_store_dwordx4 v[12:13], v[4:7], off offset:64
	v_pk_mul_f32 v[8:9], v[40:41], v[2:3] op_sel_hi:[1,0]
	v_pk_mul_f32 v[10:11], v[42:43], v[2:3] op_sel_hi:[1,0]
	v_pk_mul_f32 v[4:5], v[44:45], v[2:3] op_sel_hi:[1,0]
	v_pk_mul_f32 v[6:7], v[46:47], v[2:3] op_sel_hi:[1,0]
	v_cvt_pk_bf16_f32 v4, v4, v5
	v_cvt_pk_bf16_f32 v5, v6, v7
	v_cvt_pk_bf16_f32 v6, v8, v9
	v_cvt_pk_bf16_f32 v7, v10, v11
	s_nop 1
	v_permlane16_swap_b32 v4, v6
	v_permlane16_swap_b32 v5, v7
	global_store_dwordx4 v[12:13], v[4:7], off offset:128
	v_pk_mul_f32 v[8:9], v[32:33], v[2:3] op_sel_hi:[1,0]
	v_pk_mul_f32 v[10:11], v[34:35], v[2:3] op_sel_hi:[1,0]
	v_pk_mul_f32 v[4:5], v[36:37], v[2:3] op_sel_hi:[1,0]
	v_pk_mul_f32 v[6:7], v[38:39], v[2:3] op_sel_hi:[1,0]
	v_cvt_pk_bf16_f32 v4, v4, v5
	v_cvt_pk_bf16_f32 v5, v6, v7
	v_cvt_pk_bf16_f32 v6, v8, v9
	v_cvt_pk_bf16_f32 v7, v10, v11
	s_nop 1
	v_permlane16_swap_b32 v4, v6
	v_permlane16_swap_b32 v5, v7
	s_cmpk_lt_i32 s33, 0x100
	global_store_dwordx4 v[12:13], v[4:7], off offset:192
	s_cbranch_scc0 .LBB0_1528
